# norm phases: next row's x loads issued one row ahead (two register sets, loop unrolled by 2)
# baseline (speedup 1.0000x reference)
.LBB0_75:
	s_mul_i32 s0, s5, 0x12000
	s_mov_b32 s1, s52
	s_lshl_b64 s[0:1], s[0:1], 2
	v_readlane_b32 s4, v253, 45
	s_add_u32 s6, s4, s0
	v_readlane_b32 s0, v253, 46
	s_addc_u32 s7, s0, s1
	v_readlane_b32 s36, v253, 11
	v_writelane_b32 v254, s6, 55
	v_readlane_b32 s37, v253, 12
	s_cmp_eq_u32 s5, 0
	v_writelane_b32 v254, s7, 56
	s_mov_b64 s[0:1], s[36:37]
	s_cselect_b32 s1, s1, s71
	s_cselect_b32 s0, s0, s70
	v_writelane_b32 v254, s5, 57
	s_lshl_b32 s4, s5, 10
	s_mov_b32 s5, s52
	v_writelane_b32 v254, s4, 58
	v_mov_b32_e32 v0, v154
	v_mov_b32_e32 v2, v154
	v_writelane_b32 v254, s5, 59
	v_readlane_b32 s4, v253, 0
	v_readfirstlane_b32 s5, v2
	s_ashr_i32 s5, s5, 6
	s_lshl_b32 s4, s4, 3
	s_and_b32 s5, s5, -4
	v_lshrrev_b32_e32 v1, 6, v0
	s_add_i32 s5, s5, s4
	v_and_or_b32 v16, v1, 3, s5
	s_movk_i32 s4, 0x4000
	v_cmp_gt_i32_e32 vcc, s4, v16
	v_readlane_b32 s38, v253, 13
	v_readlane_b32 s39, v253, 14
	v_readlane_b32 s40, v253, 15
	v_readlane_b32 s41, v253, 16
	v_readlane_b32 s42, v253, 17
	v_readlane_b32 s43, v253, 18
	v_readlane_b32 s44, v253, 19
	v_readlane_b32 s45, v253, 20
	v_readlane_b32 s46, v253, 21
	v_readlane_b32 s47, v253, 22
	v_readlane_b32 s48, v253, 23
	v_readlane_b32 s49, v253, 24
	v_readlane_b32 s50, v253, 25
	v_readlane_b32 s51, v253, 26
	s_and_saveexec_b64 s[4:5], vcc
	v_readlane_b32 s10, v254, 47
	v_readlane_b32 s12, v254, 49
	s_movk_i32 s8, 0x3fff
	v_readlane_b32 s11, v254, 48
	v_readlane_b32 s13, v254, 50
	s_cbranch_execz .LBB0_78
	v_readlane_b32 s6, v254, 58
	v_readlane_b32 s7, v254, 59
	v_readlane_b32 s36, v253, 11
	s_lshl_b64 s[6:7], s[6:7], 2
	v_readlane_b32 s44, v253, 19
	v_readlane_b32 s45, v253, 20
	s_add_u32 s6, s44, s6
	v_and_b32_e32 v2, 63, v0
	s_addc_u32 s7, s45, s7
	v_lshlrev_b32_e32 v136, 5, v2
	v_lshl_add_u64 v[18:19], s[6:7], 0, v[136:137]
	v_readlane_b32 s6, v254, 55
	v_readlane_b32 s7, v254, 56
	v_lshlrev_b32_e32 v0, 2, v2
	v_ashrrev_i32_e32 v17, 31, v16
	v_lshl_add_u64 v[20:21], s[6:7], 0, v[136:137]
	s_mov_b64 s[6:7], 0x1000
	v_xor_b32_e32 v29, 64, v0
	v_xor_b32_e32 v34, 0x80, v0
	v_lshl_add_u64 v[22:23], v[20:21], 0, s[6:7]
	v_lshlrev_b64 v[0:1], 11, v[16:17]
	v_readlane_b32 s6, v253, 47
	v_lshl_or_b32 v0, v2, 4, v0
	v_readlane_b32 s7, v253, 48
	v_readlane_b32 s37, v253, 12
	v_readlane_b32 s38, v253, 13
	v_lshl_add_u64 v[24:25], s[6:7], 0, v[0:1]
	v_lshlrev_b64 v[0:1], 12, v[16:17]
	v_or_b32_e32 v0, v0, v136
	v_lshl_add_u64 v[26:27], s[0:1], 0, v[0:1]
	s_mov_b64 s[6:7], 0
	v_readlane_b32 s39, v253, 14
	v_readlane_b32 s40, v253, 15
	v_readlane_b32 s41, v253, 16
	v_readlane_b32 s42, v253, 17
	v_readlane_b32 s43, v253, 18
	v_readlane_b32 s46, v253, 21
	v_readlane_b32 s47, v253, 22
	v_readlane_b32 s48, v253, 23
	v_readlane_b32 s49, v253, 24
	v_readlane_b32 s50, v253, 25
	v_readlane_b32 s51, v253, 26
	global_load_dwordx4 v[8:11], v[26:27], off offset:16
	global_load_dwordx4 v[12:15], v[26:27], off
	global_load_dwordx4 v[4:7], v[26:27], off offset:2048
	global_load_dwordx4 v[0:3], v[26:27], off offset:2064
	v_lshl_add_u64 v[26:27], v[26:27], 0, s[12:13]
	s_sub_u32 s64, 0, s12
	v_mov_b32_e32 v134, s64
.LBB0_77:
	v_ashrrev_i32_e32 v30, 11, v16
	v_mul_hi_i32_i24_e32 v31, 0x2400, v30
	v_mul_i32_i24_e32 v30, 0x2400, v30
	v_lshlrev_b64 v[30:31], 2, v[30:31]
	v_lshl_add_u64 v[32:33], v[22:23], 0, v[30:31]
	v_lshl_add_u64 v[30:31], v[20:21], 0, v[30:31]
	global_load_dwordx4 v[36:39], v[18:19], off offset:16
	global_load_dwordx4 v[40:43], v[18:19], off
	global_load_dwordx4 v[44:47], v[32:33], off offset:16
	global_load_dwordx4 v[48:51], v[32:33], off
	global_load_dwordx4 v[52:55], v[30:31], off offset:16
	global_load_dwordx4 v[56:59], v[30:31], off
	global_load_dwordx4 v[60:63], v[18:19], off offset:2064
	global_load_dwordx4 v[64:67], v[18:19], off offset:2048
	global_load_dwordx4 v[68:71], v[32:33], off offset:2064
	global_load_dwordx4 v[72:75], v[32:33], off offset:2048
	global_load_dwordx4 v[76:79], v[30:31], off offset:2064
	global_load_dwordx4 v[80:83], v[30:31], off offset:2048
	v_add_u32_e32 v16, s20, v16
	v_cmp_lt_i32_e32 vcc, s8, v16
	s_or_b64 s[6:7], vcc, s[6:7]
	s_nop 0
	v_cndmask_b32_e32 v132, 0, v134, vcc
	v_cndmask_b32_e64 v133, 0, -1, vcc
	v_lshl_add_u64 v[132:133], v[26:27], 0, v[132:133]
	global_load_dwordx4 v[124:127], v[132:133], off offset:16
	global_load_dwordx4 v[128:131], v[132:133], off
	global_load_dwordx4 v[120:123], v[132:133], off offset:2048
	global_load_dwordx4 v[116:119], v[132:133], off offset:2064
	v_lshl_add_u64 v[26:27], v[26:27], 0, s[12:13]
	s_waitcnt vmcnt(16)
	v_mul_f32_e32 v85, v9, v9
	s_waitcnt vmcnt(16)
	v_mul_f32_e32 v84, v13, v13
	v_fmac_f32_e32 v84, v12, v12
	v_fmac_f32_e32 v85, v8, v8
	v_fmac_f32_e32 v84, v14, v14
	v_fmac_f32_e32 v85, v10, v10
	v_fmac_f32_e32 v84, v15, v15
	v_fmac_f32_e32 v85, v11, v11
	v_add_f32_e32 v17, v84, v85
	v_mov_b32_e32 v32, v5
	v_mov_b32_e32 v33, v1
	v_mov_b32_e32 v30, v4
	v_mov_b32_e32 v31, v0
	v_pk_mul_f32 v[32:33], v[32:33], v[32:33]
	s_nop 0
	v_pk_fma_f32 v[30:31], v[30:31], v[30:31], v[32:33]
	v_mov_b32_e32 v32, v6
	v_mov_b32_e32 v33, v2
	v_pk_fma_f32 v[30:31], v[32:33], v[32:33], v[30:31]
	v_mov_b32_e32 v32, v7
	v_mov_b32_e32 v33, v3
	v_pk_fma_f32 v[30:31], v[32:33], v[32:33], v[30:31]
	s_nop 0
	v_add_f32_e32 v17, v17, v30
	v_add_f32_e32 v17, v17, v31
	s_nop 1
	v_add_f32_dpp v17, v17, v17 quad_perm:[1,0,3,2] row_mask:0xf bank_mask:0xf bound_ctrl:1
	s_nop 0
	s_nop 0
	v_add_f32_dpp v17, v17, v17 quad_perm:[2,3,0,1] row_mask:0xf bank_mask:0xf bound_ctrl:1
	s_nop 0
	s_nop 0
	v_add_f32_dpp v17, v17, v17 row_half_mirror row_mask:0xf bank_mask:0xf bound_ctrl:1
	s_nop 1
	v_add_f32_dpp v17, v17, v17 row_mirror row_mask:0xf bank_mask:0xf bound_ctrl:1
	ds_bpermute_b32 v28, v29, v17
	s_waitcnt lgkmcnt(0)
	v_add_f32_e32 v17, v17, v28
	ds_bpermute_b32 v28, v34, v17
	s_waitcnt lgkmcnt(0)
	v_add_f32_e32 v17, v17, v28
	v_fmamk_f32 v17, v17, 0x3a800000, v155
	v_rsq_f32_e32 v28, v17
	s_nop 0
	v_pk_mul_f32 v[8:9], v[8:9], v[28:29] op_sel_hi:[1,0]
	v_pk_mul_f32 v[12:13], v[12:13], v[28:29] op_sel_hi:[1,0]
	v_pk_mul_f32 v[14:15], v[14:15], v[28:29] op_sel_hi:[1,0]
	v_pk_mul_f32 v[0:1], v[0:1], v[28:29] op_sel_hi:[1,0]
	v_pk_mul_f32 v[4:5], v[4:5], v[28:29] op_sel_hi:[1,0]
	v_pk_mul_f32 v[6:7], v[6:7], v[28:29] op_sel_hi:[1,0]
	s_waitcnt vmcnt(15)
	v_pk_mul_f32 v[8:9], v[36:37], v[8:9]
	s_waitcnt vmcnt(14)
	v_pk_mul_f32 v[12:13], v[40:41], v[12:13]
	s_waitcnt vmcnt(13)
	v_pk_add_f32 v[36:37], v[44:45], 1.0 op_sel_hi:[1,0]
	s_waitcnt vmcnt(12)
	v_pk_add_f32 v[40:41], v[48:49], 1.0 op_sel_hi:[1,0]
	s_waitcnt vmcnt(11)
	v_pk_fma_f32 v[36:37], v[36:37], v[8:9], v[52:53]
	v_pk_mul_f32 v[8:9], v[10:11], v[28:29] op_sel_hi:[1,0]
	s_waitcnt vmcnt(10)
	v_pk_fma_f32 v[12:13], v[40:41], v[12:13], v[56:57]
	v_pk_mul_f32 v[14:15], v[42:43], v[14:15]
	v_pk_add_f32 v[40:41], v[50:51], 1.0 op_sel_hi:[1,0]
	v_pk_mul_f32 v[8:9], v[38:39], v[8:9]
	v_pk_add_f32 v[10:11], v[46:47], 1.0 op_sel_hi:[1,0]
	v_pk_fma_f32 v[14:15], v[40:41], v[14:15], v[58:59]
	v_pk_fma_f32 v[38:39], v[10:11], v[8:9], v[54:55]
	v_cvt_pk_bf16_f32 v8, v12, v13
	v_cvt_pk_bf16_f32 v9, v14, v15
	v_cvt_pk_bf16_f32 v10, v36, v37
	v_cvt_pk_bf16_f32 v11, v38, v39
	global_store_dwordx4 v[24:25], v[8:11], off
	s_waitcnt vmcnt(10)
	v_pk_mul_f32 v[0:1], v[0:1], v[60:61]
	s_waitcnt vmcnt(9)
	v_pk_mul_f32 v[4:5], v[64:65], v[4:5]
	s_waitcnt vmcnt(8)
	v_pk_add_f32 v[60:61], v[68:69], 1.0 op_sel_hi:[1,0]
	s_waitcnt vmcnt(7)
	v_pk_add_f32 v[64:65], v[72:73], 1.0 op_sel_hi:[1,0]
	s_waitcnt vmcnt(6)
	v_pk_fma_f32 v[60:61], v[0:1], v[60:61], v[76:77]
	v_pk_mul_f32 v[0:1], v[2:3], v[28:29] op_sel_hi:[1,0]
	s_waitcnt vmcnt(5)
	v_pk_fma_f32 v[4:5], v[64:65], v[4:5], v[80:81]
	v_pk_mul_f32 v[6:7], v[66:67], v[6:7]
	v_pk_add_f32 v[64:65], v[74:75], 1.0 op_sel_hi:[1,0]
	v_pk_mul_f32 v[0:1], v[0:1], v[62:63]
	v_pk_add_f32 v[2:3], v[70:71], 1.0 op_sel_hi:[1,0]
	v_pk_fma_f32 v[6:7], v[64:65], v[6:7], v[82:83]
	v_pk_fma_f32 v[62:63], v[0:1], v[2:3], v[78:79]
	v_cvt_pk_bf16_f32 v0, v4, v5
	v_cvt_pk_bf16_f32 v1, v6, v7
	v_cvt_pk_bf16_f32 v2, v60, v61
	v_cvt_pk_bf16_f32 v3, v62, v63
	global_store_dwordx4 v[24:25], v[0:3], off offset:1024
	v_lshl_add_u64 v[24:25], v[24:25], 0, s[10:11]
	s_andn2_b64 exec, exec, s[6:7]
	s_cbranch_execz .Lnorm_done_a
	v_ashrrev_i32_e32 v30, 11, v16
	v_mul_hi_i32_i24_e32 v31, 0x2400, v30
	v_mul_i32_i24_e32 v30, 0x2400, v30
	v_lshlrev_b64 v[30:31], 2, v[30:31]
	v_lshl_add_u64 v[32:33], v[22:23], 0, v[30:31]
	v_lshl_add_u64 v[30:31], v[20:21], 0, v[30:31]
	global_load_dwordx4 v[36:39], v[18:19], off offset:16
	global_load_dwordx4 v[40:43], v[18:19], off
	global_load_dwordx4 v[44:47], v[32:33], off offset:16
	global_load_dwordx4 v[48:51], v[32:33], off
	global_load_dwordx4 v[52:55], v[30:31], off offset:16
	global_load_dwordx4 v[56:59], v[30:31], off
	global_load_dwordx4 v[60:63], v[18:19], off offset:2064
	global_load_dwordx4 v[64:67], v[18:19], off offset:2048
	global_load_dwordx4 v[68:71], v[32:33], off offset:2064
	global_load_dwordx4 v[72:75], v[32:33], off offset:2048
	global_load_dwordx4 v[76:79], v[30:31], off offset:2064
	global_load_dwordx4 v[80:83], v[30:31], off offset:2048
	v_add_u32_e32 v16, s20, v16
	v_cmp_lt_i32_e32 vcc, s8, v16
	s_or_b64 s[6:7], vcc, s[6:7]
	s_nop 0
	v_cndmask_b32_e32 v132, 0, v134, vcc
	v_cndmask_b32_e64 v133, 0, -1, vcc
	v_lshl_add_u64 v[132:133], v[26:27], 0, v[132:133]
	global_load_dwordx4 v[8:11], v[132:133], off offset:16
	global_load_dwordx4 v[12:15], v[132:133], off
	global_load_dwordx4 v[4:7], v[132:133], off offset:2048
	global_load_dwordx4 v[0:3], v[132:133], off offset:2064
	v_lshl_add_u64 v[26:27], v[26:27], 0, s[12:13]
	s_waitcnt vmcnt(16)
	v_mul_f32_e32 v85, v125, v125
	s_waitcnt vmcnt(16)
	v_mul_f32_e32 v84, v129, v129
	v_fmac_f32_e32 v84, v128, v128
	v_fmac_f32_e32 v85, v124, v124
	v_fmac_f32_e32 v84, v130, v130
	v_fmac_f32_e32 v85, v126, v126
	v_fmac_f32_e32 v84, v131, v131
	v_fmac_f32_e32 v85, v127, v127
	v_add_f32_e32 v17, v84, v85
	v_mov_b32_e32 v32, v121
	v_mov_b32_e32 v33, v117
	v_mov_b32_e32 v30, v120
	v_mov_b32_e32 v31, v116
	v_pk_mul_f32 v[32:33], v[32:33], v[32:33]
	s_nop 0
	v_pk_fma_f32 v[30:31], v[30:31], v[30:31], v[32:33]
	v_mov_b32_e32 v32, v122
	v_mov_b32_e32 v33, v118
	v_pk_fma_f32 v[30:31], v[32:33], v[32:33], v[30:31]
	v_mov_b32_e32 v32, v123
	v_mov_b32_e32 v33, v119
	v_pk_fma_f32 v[30:31], v[32:33], v[32:33], v[30:31]
	s_nop 0
	v_add_f32_e32 v17, v17, v30
	v_add_f32_e32 v17, v17, v31
	s_nop 1
	v_add_f32_dpp v17, v17, v17 quad_perm:[1,0,3,2] row_mask:0xf bank_mask:0xf bound_ctrl:1
	s_nop 0
	s_nop 0
	v_add_f32_dpp v17, v17, v17 quad_perm:[2,3,0,1] row_mask:0xf bank_mask:0xf bound_ctrl:1
	s_nop 0
	s_nop 0
	v_add_f32_dpp v17, v17, v17 row_half_mirror row_mask:0xf bank_mask:0xf bound_ctrl:1
	s_nop 1
	v_add_f32_dpp v17, v17, v17 row_mirror row_mask:0xf bank_mask:0xf bound_ctrl:1
	ds_bpermute_b32 v28, v29, v17
	s_waitcnt lgkmcnt(0)
	v_add_f32_e32 v17, v17, v28
	ds_bpermute_b32 v28, v34, v17
	s_waitcnt lgkmcnt(0)
	v_add_f32_e32 v17, v17, v28
	v_fmamk_f32 v17, v17, 0x3a800000, v155
	v_rsq_f32_e32 v28, v17
	s_nop 0
	v_pk_mul_f32 v[124:125], v[124:125], v[28:29] op_sel_hi:[1,0]
	v_pk_mul_f32 v[128:129], v[128:129], v[28:29] op_sel_hi:[1,0]
	v_pk_mul_f32 v[130:131], v[130:131], v[28:29] op_sel_hi:[1,0]
	v_pk_mul_f32 v[116:117], v[116:117], v[28:29] op_sel_hi:[1,0]
	v_pk_mul_f32 v[120:121], v[120:121], v[28:29] op_sel_hi:[1,0]
	v_pk_mul_f32 v[122:123], v[122:123], v[28:29] op_sel_hi:[1,0]
	s_waitcnt vmcnt(15)
	v_pk_mul_f32 v[124:125], v[36:37], v[124:125]
	s_waitcnt vmcnt(14)
	v_pk_mul_f32 v[128:129], v[40:41], v[128:129]
	s_waitcnt vmcnt(13)
	v_pk_add_f32 v[36:37], v[44:45], 1.0 op_sel_hi:[1,0]
	s_waitcnt vmcnt(12)
	v_pk_add_f32 v[40:41], v[48:49], 1.0 op_sel_hi:[1,0]
	s_waitcnt vmcnt(11)
	v_pk_fma_f32 v[36:37], v[36:37], v[124:125], v[52:53]
	v_pk_mul_f32 v[124:125], v[126:127], v[28:29] op_sel_hi:[1,0]
	s_waitcnt vmcnt(10)
	v_pk_fma_f32 v[128:129], v[40:41], v[128:129], v[56:57]
	v_pk_mul_f32 v[130:131], v[42:43], v[130:131]
	v_pk_add_f32 v[40:41], v[50:51], 1.0 op_sel_hi:[1,0]
	v_pk_mul_f32 v[124:125], v[38:39], v[124:125]
	v_pk_add_f32 v[126:127], v[46:47], 1.0 op_sel_hi:[1,0]
	v_pk_fma_f32 v[130:131], v[40:41], v[130:131], v[58:59]
	v_pk_fma_f32 v[38:39], v[126:127], v[124:125], v[54:55]
	v_cvt_pk_bf16_f32 v124, v128, v129
	v_cvt_pk_bf16_f32 v125, v130, v131
	v_cvt_pk_bf16_f32 v126, v36, v37
	v_cvt_pk_bf16_f32 v127, v38, v39
	global_store_dwordx4 v[24:25], v[124:127], off
	s_waitcnt vmcnt(10)
	v_pk_mul_f32 v[116:117], v[116:117], v[60:61]
	s_waitcnt vmcnt(9)
	v_pk_mul_f32 v[120:121], v[64:65], v[120:121]
	s_waitcnt vmcnt(8)
	v_pk_add_f32 v[60:61], v[68:69], 1.0 op_sel_hi:[1,0]
	s_waitcnt vmcnt(7)
	v_pk_add_f32 v[64:65], v[72:73], 1.0 op_sel_hi:[1,0]
	s_waitcnt vmcnt(6)
	v_pk_fma_f32 v[60:61], v[116:117], v[60:61], v[76:77]
	v_pk_mul_f32 v[116:117], v[118:119], v[28:29] op_sel_hi:[1,0]
	s_waitcnt vmcnt(5)
	v_pk_fma_f32 v[120:121], v[64:65], v[120:121], v[80:81]
	v_pk_mul_f32 v[122:123], v[66:67], v[122:123]
	v_pk_add_f32 v[64:65], v[74:75], 1.0 op_sel_hi:[1,0]
	v_pk_mul_f32 v[116:117], v[116:117], v[62:63]
	v_pk_add_f32 v[118:119], v[70:71], 1.0 op_sel_hi:[1,0]
	v_pk_fma_f32 v[122:123], v[64:65], v[122:123], v[82:83]
	v_pk_fma_f32 v[62:63], v[116:117], v[118:119], v[78:79]
	v_cvt_pk_bf16_f32 v116, v120, v121
	v_cvt_pk_bf16_f32 v117, v122, v123
	v_cvt_pk_bf16_f32 v118, v60, v61
	v_cvt_pk_bf16_f32 v119, v62, v63
	global_store_dwordx4 v[24:25], v[116:119], off offset:1024
	v_lshl_add_u64 v[24:25], v[24:25], 0, s[10:11]
	s_andn2_b64 exec, exec, s[6:7]
	s_cbranch_execnz .LBB0_77
.Lnorm_done_a:
.LBB0_78:
	s_or_b64 exec, exec, s[4:5]
	s_getreg_b32 s8, hwreg(HW_REG_XCC_ID, 0, 4)
	s_waitcnt vmcnt(0)
	s_barrier
	s_mov_b64 s[4:5], exec
	v_readlane_b32 s6, v253, 9
	v_readlane_b32 s7, v253, 10
	s_and_b64 s[6:7], s[4:5], s[6:7]
	s_mov_b64 exec, s[6:7]
	s_cbranch_execz .LBB0_108
	v_readlane_b32 s6, v253, 43
	s_lshl_b32 s8, s8, 8
	v_readlane_b32 s7, v253, 44
	s_and_b32 s8, s8, 0xf00
	s_add_u32 s13, s6, s8
	s_addc_u32 s12, s7, 0
	v_mov_b32_e32 v0, s13
	v_add_co_u32_e32 v2, vcc, 0x1000, v0
	v_mov_b32_e32 v0, s12
	s_nop 0
	v_addc_co_u32_e32 v3, vcc, 0, v0, vcc
	s_waitcnt vmcnt(0) expcnt(0) lgkmcnt(0)
	ds_read_b32 v4, v156
	ds_read_b32 v1, v157
	flat_atomic_add v2, v[2:3], v158 offset:1024 sc0
	s_waitcnt lgkmcnt(0)
	v_cvt_f32_u32_e32 v0, v4
	v_sub_u32_e32 v3, 0, v4
	v_rcp_iflag_f32_e32 v0, v0
	s_nop 0
	v_mul_f32_e32 v0, 0x4f7ffffe, v0
	v_cvt_u32_f32_e32 v0, v0
	v_mul_lo_u32 v3, v3, v0
	v_mul_hi_u32 v3, v0, v3
	v_add_u32_e32 v0, v0, v3
	s_waitcnt vmcnt(0)
	v_mul_hi_u32 v0, v2, v0
	v_mul_lo_u32 v3, v0, v4
	v_sub_u32_e32 v3, v2, v3
	v_add_u32_e32 v5, 1, v0
	v_cmp_ge_u32_e32 vcc, v3, v4
	v_add_u32_e32 v2, 1, v2
	s_nop 0
	v_cndmask_b32_e32 v0, v0, v5, vcc
	v_sub_u32_e32 v5, v3, v4
	v_cndmask_b32_e32 v3, v3, v5, vcc
	v_add_u32_e32 v5, 1, v0
	v_cmp_ge_u32_e32 vcc, v3, v4
	s_nop 1
	v_cndmask_b32_e32 v0, v0, v5, vcc
	v_mul_lo_u32 v3, v4, v0
	v_add_u32_e32 v3, v3, v4
	v_cmp_ne_u32_e32 vcc, v2, v3
	s_and_saveexec_b64 s[8:9], vcc
	s_xor_b64 s[8:9], exec, s[8:9]
	s_cbranch_execz .LBB0_92
	v_mov_b32_e32 v1, s13
	v_add_co_u32_e32 v2, vcc, 0x2000, v1
	v_mov_b32_e32 v1, s12
	s_nop 0
	v_addc_co_u32_e32 v3, vcc, 0, v1, vcc
	flat_load_dword v1, v[2:3] offset:1024 sc1
	s_add_u32 s14, s13, 0x2400
	s_addc_u32 s15, s12, 0
	s_waitcnt vmcnt(0) lgkmcnt(0)
	v_cmp_eq_u32_e32 vcc, v1, v0
	s_and_saveexec_b64 s[10:11], vcc
	s_cbranch_execz .LBB0_91
	s_mov_b32 s21, 1
	s_mov_b64 s[26:27], 0
	s_branch .LBB0_83

.LBB0_186:
	s_or_b64 exec, exec, s[0:1]
	v_mov_b32_e32 v0, v154
	v_mov_b32_e32 v2, v154
	s_waitcnt lgkmcnt(0)
	s_barrier
	v_readlane_b32 s0, v253, 0
	v_readfirstlane_b32 s1, v2
	s_ashr_i32 s1, s1, 6
	s_lshl_b32 s0, s0, 3
	s_and_b32 s1, s1, -4
	v_lshrrev_b32_e32 v1, 6, v0
	s_add_i32 s1, s1, s0
	v_and_or_b32 v16, v1, 3, s1
	s_movk_i32 s0, 0x4000
	v_cmp_gt_i32_e32 vcc, s0, v16
	s_and_saveexec_b64 s[0:1], vcc
	v_readlane_b32 s8, v254, 47
	v_readlane_b32 s10, v254, 49
	s_movk_i32 s6, 0x3fff
	v_readlane_b32 s9, v254, 48
	v_readlane_b32 s11, v254, 50
	s_cbranch_execz .LBB0_189
	v_readlane_b32 s4, v254, 58
	v_readlane_b32 s5, v254, 59
	v_readlane_b32 s36, v253, 11
	s_lshl_b64 s[4:5], s[4:5], 2
	v_readlane_b32 s50, v253, 25
	v_readlane_b32 s51, v253, 26
	s_add_u32 s4, s50, s4
	v_and_b32_e32 v2, 63, v0
	s_addc_u32 s5, s51, s5
	v_lshlrev_b32_e32 v136, 5, v2
	v_lshl_add_u64 v[18:19], s[4:5], 0, v[136:137]
	v_readlane_b32 s4, v254, 55
	v_lshlrev_b32_e32 v0, 2, v2
	v_readlane_b32 s5, v254, 56
	v_xor_b32_e32 v29, 64, v0
	v_xor_b32_e32 v34, 0x80, v0
	v_lshl_add_u64 v[0:1], s[4:5], 0, v[136:137]
	s_mov_b64 s[4:5], 0x4000
	v_lshl_add_u64 v[20:21], v[0:1], 0, s[4:5]
	s_mov_b64 s[4:5], 0x3000
	v_ashrrev_i32_e32 v17, 31, v16
	v_lshl_add_u64 v[22:23], v[0:1], 0, s[4:5]
	v_lshlrev_b64 v[0:1], 11, v[16:17]
	v_readlane_b32 s4, v253, 47
	v_lshl_or_b32 v0, v2, 4, v0
	v_readlane_b32 s5, v253, 48
	v_readlane_b32 s37, v253, 12
	v_readlane_b32 s38, v253, 13
	v_lshl_add_u64 v[24:25], s[4:5], 0, v[0:1]
	v_lshlrev_b64 v[0:1], 12, v[16:17]
	v_or_b32_e32 v0, v0, v136
	v_lshl_add_u64 v[26:27], s[70:71], 0, v[0:1]
	s_mov_b64 s[4:5], 0
	v_readlane_b32 s39, v253, 14
	v_readlane_b32 s40, v253, 15
	v_readlane_b32 s41, v253, 16
	v_readlane_b32 s42, v253, 17
	v_readlane_b32 s43, v253, 18
	v_readlane_b32 s44, v253, 19
	v_readlane_b32 s45, v253, 20
	v_readlane_b32 s46, v253, 21
	v_readlane_b32 s47, v253, 22
	v_readlane_b32 s48, v253, 23
	v_readlane_b32 s49, v253, 24
	global_load_dwordx4 v[8:11], v[26:27], off offset:16
	global_load_dwordx4 v[12:15], v[26:27], off
	global_load_dwordx4 v[4:7], v[26:27], off offset:2048
	global_load_dwordx4 v[0:3], v[26:27], off offset:2064
	v_lshl_add_u64 v[26:27], v[26:27], 0, s[10:11]
	s_sub_u32 s64, 0, s10
	v_mov_b32_e32 v134, s64
.LBB0_188:
	v_ashrrev_i32_e32 v30, 11, v16
	v_mul_hi_i32_i24_e32 v31, 0x2400, v30
	v_mul_i32_i24_e32 v30, 0x2400, v30
	v_lshlrev_b64 v[30:31], 2, v[30:31]
	v_lshl_add_u64 v[32:33], v[20:21], 0, v[30:31]
	v_lshl_add_u64 v[30:31], v[22:23], 0, v[30:31]
	global_load_dwordx4 v[36:39], v[18:19], off offset:16
	global_load_dwordx4 v[40:43], v[18:19], off
	global_load_dwordx4 v[44:47], v[32:33], off offset:16
	global_load_dwordx4 v[48:51], v[32:33], off
	global_load_dwordx4 v[52:55], v[30:31], off offset:16
	global_load_dwordx4 v[56:59], v[30:31], off
	global_load_dwordx4 v[60:63], v[18:19], off offset:2064
	global_load_dwordx4 v[64:67], v[18:19], off offset:2048
	global_load_dwordx4 v[68:71], v[32:33], off offset:2064
	global_load_dwordx4 v[72:75], v[32:33], off offset:2048
	global_load_dwordx4 v[76:79], v[30:31], off offset:2064
	global_load_dwordx4 v[80:83], v[30:31], off offset:2048
	v_add_u32_e32 v16, s20, v16
	v_cmp_lt_i32_e32 vcc, s6, v16
	s_or_b64 s[4:5], vcc, s[4:5]
	s_nop 0
	v_cndmask_b32_e32 v132, 0, v134, vcc
	v_cndmask_b32_e64 v133, 0, -1, vcc
	v_lshl_add_u64 v[132:133], v[26:27], 0, v[132:133]
	global_load_dwordx4 v[124:127], v[132:133], off offset:16
	global_load_dwordx4 v[128:131], v[132:133], off
	global_load_dwordx4 v[120:123], v[132:133], off offset:2048
	global_load_dwordx4 v[116:119], v[132:133], off offset:2064
	v_lshl_add_u64 v[26:27], v[26:27], 0, s[10:11]
	s_waitcnt vmcnt(16)
	v_mul_f32_e32 v85, v9, v9
	v_mul_f32_e32 v84, v13, v13
	v_fmac_f32_e32 v84, v12, v12
	v_fmac_f32_e32 v85, v8, v8
	v_fmac_f32_e32 v84, v14, v14
	v_fmac_f32_e32 v85, v10, v10
	v_fmac_f32_e32 v84, v15, v15
	v_fmac_f32_e32 v85, v11, v11
	v_add_f32_e32 v17, v84, v85
	v_mov_b32_e32 v32, v5
	v_mov_b32_e32 v33, v1
	v_mov_b32_e32 v30, v4
	v_mov_b32_e32 v31, v0
	v_pk_mul_f32 v[32:33], v[32:33], v[32:33]
	s_nop 0
	v_pk_fma_f32 v[30:31], v[30:31], v[30:31], v[32:33]
	v_mov_b32_e32 v32, v6
	v_mov_b32_e32 v33, v2
	v_pk_fma_f32 v[30:31], v[32:33], v[32:33], v[30:31]
	v_mov_b32_e32 v32, v7
	v_mov_b32_e32 v33, v3
	v_pk_fma_f32 v[30:31], v[32:33], v[32:33], v[30:31]
	s_nop 0
	v_add_f32_e32 v17, v17, v30
	v_add_f32_e32 v17, v17, v31
	s_nop 1
	v_add_f32_dpp v17, v17, v17 quad_perm:[1,0,3,2] row_mask:0xf bank_mask:0xf bound_ctrl:1
	s_nop 0
	s_nop 0
	v_add_f32_dpp v17, v17, v17 quad_perm:[2,3,0,1] row_mask:0xf bank_mask:0xf bound_ctrl:1
	s_nop 0
	s_nop 0
	v_add_f32_dpp v17, v17, v17 row_half_mirror row_mask:0xf bank_mask:0xf bound_ctrl:1
	s_nop 1
	v_add_f32_dpp v17, v17, v17 row_mirror row_mask:0xf bank_mask:0xf bound_ctrl:1
	ds_bpermute_b32 v28, v29, v17
	s_waitcnt lgkmcnt(0)
	v_add_f32_e32 v17, v17, v28
	ds_bpermute_b32 v28, v34, v17
	s_waitcnt lgkmcnt(0)
	v_add_f32_e32 v17, v17, v28
	v_fmamk_f32 v17, v17, 0x3a800000, v155
	v_rsq_f32_e32 v28, v17
	s_nop 0
	v_pk_mul_f32 v[8:9], v[8:9], v[28:29] op_sel_hi:[1,0]
	v_pk_mul_f32 v[12:13], v[12:13], v[28:29] op_sel_hi:[1,0]
	v_pk_mul_f32 v[14:15], v[14:15], v[28:29] op_sel_hi:[1,0]
	v_pk_mul_f32 v[0:1], v[0:1], v[28:29] op_sel_hi:[1,0]
	v_pk_mul_f32 v[4:5], v[4:5], v[28:29] op_sel_hi:[1,0]
	v_pk_mul_f32 v[6:7], v[6:7], v[28:29] op_sel_hi:[1,0]
	s_waitcnt vmcnt(15)
	v_pk_mul_f32 v[8:9], v[36:37], v[8:9]
	s_waitcnt vmcnt(14)
	v_pk_mul_f32 v[12:13], v[40:41], v[12:13]
	s_waitcnt vmcnt(13)
	v_pk_add_f32 v[36:37], v[44:45], 1.0 op_sel_hi:[1,0]
	s_waitcnt vmcnt(12)
	v_pk_add_f32 v[40:41], v[48:49], 1.0 op_sel_hi:[1,0]
	s_waitcnt vmcnt(11)
	v_pk_fma_f32 v[36:37], v[36:37], v[8:9], v[52:53]
	v_pk_mul_f32 v[8:9], v[10:11], v[28:29] op_sel_hi:[1,0]
	s_waitcnt vmcnt(10)
	v_pk_fma_f32 v[12:13], v[40:41], v[12:13], v[56:57]
	v_pk_mul_f32 v[14:15], v[42:43], v[14:15]
	v_pk_add_f32 v[40:41], v[50:51], 1.0 op_sel_hi:[1,0]
	v_pk_mul_f32 v[8:9], v[38:39], v[8:9]
	v_pk_add_f32 v[10:11], v[46:47], 1.0 op_sel_hi:[1,0]
	v_pk_fma_f32 v[14:15], v[40:41], v[14:15], v[58:59]
	v_pk_fma_f32 v[38:39], v[10:11], v[8:9], v[54:55]
	v_cvt_pk_bf16_f32 v8, v12, v13
	v_cvt_pk_bf16_f32 v9, v14, v15
	v_cvt_pk_bf16_f32 v10, v36, v37
	v_cvt_pk_bf16_f32 v11, v38, v39
	global_store_dwordx4 v[24:25], v[8:11], off
	s_waitcnt vmcnt(10)
	v_pk_mul_f32 v[0:1], v[0:1], v[60:61]
	s_waitcnt vmcnt(9)
	v_pk_mul_f32 v[4:5], v[64:65], v[4:5]
	s_waitcnt vmcnt(8)
	v_pk_add_f32 v[60:61], v[68:69], 1.0 op_sel_hi:[1,0]
	s_waitcnt vmcnt(7)
	v_pk_add_f32 v[64:65], v[72:73], 1.0 op_sel_hi:[1,0]
	s_waitcnt vmcnt(6)
	v_pk_fma_f32 v[60:61], v[0:1], v[60:61], v[76:77]
	v_pk_mul_f32 v[0:1], v[2:3], v[28:29] op_sel_hi:[1,0]
	s_waitcnt vmcnt(5)
	v_pk_fma_f32 v[4:5], v[64:65], v[4:5], v[80:81]
	v_pk_mul_f32 v[6:7], v[66:67], v[6:7]
	v_pk_add_f32 v[64:65], v[74:75], 1.0 op_sel_hi:[1,0]
	v_pk_mul_f32 v[0:1], v[0:1], v[62:63]
	v_pk_add_f32 v[2:3], v[70:71], 1.0 op_sel_hi:[1,0]
	v_pk_fma_f32 v[6:7], v[64:65], v[6:7], v[82:83]
	v_pk_fma_f32 v[62:63], v[0:1], v[2:3], v[78:79]
	v_cvt_pk_bf16_f32 v0, v4, v5
	v_cvt_pk_bf16_f32 v1, v6, v7
	v_cvt_pk_bf16_f32 v2, v60, v61
	v_cvt_pk_bf16_f32 v3, v62, v63
	global_store_dwordx4 v[24:25], v[0:3], off offset:1024
	v_lshl_add_u64 v[24:25], v[24:25], 0, s[8:9]
	s_andn2_b64 exec, exec, s[4:5]
	s_cbranch_execz .Lnorm_done_b
	v_ashrrev_i32_e32 v30, 11, v16
	v_mul_hi_i32_i24_e32 v31, 0x2400, v30
	v_mul_i32_i24_e32 v30, 0x2400, v30
	v_lshlrev_b64 v[30:31], 2, v[30:31]
	v_lshl_add_u64 v[32:33], v[20:21], 0, v[30:31]
	v_lshl_add_u64 v[30:31], v[22:23], 0, v[30:31]
	global_load_dwordx4 v[36:39], v[18:19], off offset:16
	global_load_dwordx4 v[40:43], v[18:19], off
	global_load_dwordx4 v[44:47], v[32:33], off offset:16
	global_load_dwordx4 v[48:51], v[32:33], off
	global_load_dwordx4 v[52:55], v[30:31], off offset:16
	global_load_dwordx4 v[56:59], v[30:31], off
	global_load_dwordx4 v[60:63], v[18:19], off offset:2064
	global_load_dwordx4 v[64:67], v[18:19], off offset:2048
	global_load_dwordx4 v[68:71], v[32:33], off offset:2064
	global_load_dwordx4 v[72:75], v[32:33], off offset:2048
	global_load_dwordx4 v[76:79], v[30:31], off offset:2064
	global_load_dwordx4 v[80:83], v[30:31], off offset:2048
	v_add_u32_e32 v16, s20, v16
	v_cmp_lt_i32_e32 vcc, s6, v16
	s_or_b64 s[4:5], vcc, s[4:5]
	s_nop 0
	v_cndmask_b32_e32 v132, 0, v134, vcc
	v_cndmask_b32_e64 v133, 0, -1, vcc
	v_lshl_add_u64 v[132:133], v[26:27], 0, v[132:133]
	global_load_dwordx4 v[8:11], v[132:133], off offset:16
	global_load_dwordx4 v[12:15], v[132:133], off
	global_load_dwordx4 v[4:7], v[132:133], off offset:2048
	global_load_dwordx4 v[0:3], v[132:133], off offset:2064
	v_lshl_add_u64 v[26:27], v[26:27], 0, s[10:11]
	s_waitcnt vmcnt(16)
	v_mul_f32_e32 v85, v125, v125
	v_mul_f32_e32 v84, v129, v129
	v_fmac_f32_e32 v84, v128, v128
	v_fmac_f32_e32 v85, v124, v124
	v_fmac_f32_e32 v84, v130, v130
	v_fmac_f32_e32 v85, v126, v126
	v_fmac_f32_e32 v84, v131, v131
	v_fmac_f32_e32 v85, v127, v127
	v_add_f32_e32 v17, v84, v85
	v_mov_b32_e32 v32, v121
	v_mov_b32_e32 v33, v117
	v_mov_b32_e32 v30, v120
	v_mov_b32_e32 v31, v116
	v_pk_mul_f32 v[32:33], v[32:33], v[32:33]
	s_nop 0
	v_pk_fma_f32 v[30:31], v[30:31], v[30:31], v[32:33]
	v_mov_b32_e32 v32, v122
	v_mov_b32_e32 v33, v118
	v_pk_fma_f32 v[30:31], v[32:33], v[32:33], v[30:31]
	v_mov_b32_e32 v32, v123
	v_mov_b32_e32 v33, v119
	v_pk_fma_f32 v[30:31], v[32:33], v[32:33], v[30:31]
	s_nop 0
	v_add_f32_e32 v17, v17, v30
	v_add_f32_e32 v17, v17, v31
	s_nop 1
	v_add_f32_dpp v17, v17, v17 quad_perm:[1,0,3,2] row_mask:0xf bank_mask:0xf bound_ctrl:1
	s_nop 0
	s_nop 0
	v_add_f32_dpp v17, v17, v17 quad_perm:[2,3,0,1] row_mask:0xf bank_mask:0xf bound_ctrl:1
	s_nop 0
	s_nop 0
	v_add_f32_dpp v17, v17, v17 row_half_mirror row_mask:0xf bank_mask:0xf bound_ctrl:1
	s_nop 1
	v_add_f32_dpp v17, v17, v17 row_mirror row_mask:0xf bank_mask:0xf bound_ctrl:1
	ds_bpermute_b32 v28, v29, v17
	s_waitcnt lgkmcnt(0)
	v_add_f32_e32 v17, v17, v28
	ds_bpermute_b32 v28, v34, v17
	s_waitcnt lgkmcnt(0)
	v_add_f32_e32 v17, v17, v28
	v_fmamk_f32 v17, v17, 0x3a800000, v155
	v_rsq_f32_e32 v28, v17
	s_nop 0
	v_pk_mul_f32 v[124:125], v[124:125], v[28:29] op_sel_hi:[1,0]
	v_pk_mul_f32 v[128:129], v[128:129], v[28:29] op_sel_hi:[1,0]
	v_pk_mul_f32 v[130:131], v[130:131], v[28:29] op_sel_hi:[1,0]
	v_pk_mul_f32 v[116:117], v[116:117], v[28:29] op_sel_hi:[1,0]
	v_pk_mul_f32 v[120:121], v[120:121], v[28:29] op_sel_hi:[1,0]
	v_pk_mul_f32 v[122:123], v[122:123], v[28:29] op_sel_hi:[1,0]
	s_waitcnt vmcnt(15)
	v_pk_mul_f32 v[124:125], v[36:37], v[124:125]
	s_waitcnt vmcnt(14)
	v_pk_mul_f32 v[128:129], v[40:41], v[128:129]
	s_waitcnt vmcnt(13)
	v_pk_add_f32 v[36:37], v[44:45], 1.0 op_sel_hi:[1,0]
	s_waitcnt vmcnt(12)
	v_pk_add_f32 v[40:41], v[48:49], 1.0 op_sel_hi:[1,0]
	s_waitcnt vmcnt(11)
	v_pk_fma_f32 v[36:37], v[36:37], v[124:125], v[52:53]
	v_pk_mul_f32 v[124:125], v[126:127], v[28:29] op_sel_hi:[1,0]
	s_waitcnt vmcnt(10)
	v_pk_fma_f32 v[128:129], v[40:41], v[128:129], v[56:57]
	v_pk_mul_f32 v[130:131], v[42:43], v[130:131]
	v_pk_add_f32 v[40:41], v[50:51], 1.0 op_sel_hi:[1,0]
	v_pk_mul_f32 v[124:125], v[38:39], v[124:125]
	v_pk_add_f32 v[126:127], v[46:47], 1.0 op_sel_hi:[1,0]
	v_pk_fma_f32 v[130:131], v[40:41], v[130:131], v[58:59]
	v_pk_fma_f32 v[38:39], v[126:127], v[124:125], v[54:55]
	v_cvt_pk_bf16_f32 v124, v128, v129
	v_cvt_pk_bf16_f32 v125, v130, v131
	v_cvt_pk_bf16_f32 v126, v36, v37
	v_cvt_pk_bf16_f32 v127, v38, v39
	global_store_dwordx4 v[24:25], v[124:127], off
	s_waitcnt vmcnt(10)
	v_pk_mul_f32 v[116:117], v[116:117], v[60:61]
	s_waitcnt vmcnt(9)
	v_pk_mul_f32 v[120:121], v[64:65], v[120:121]
	s_waitcnt vmcnt(8)
	v_pk_add_f32 v[60:61], v[68:69], 1.0 op_sel_hi:[1,0]
	s_waitcnt vmcnt(7)
	v_pk_add_f32 v[64:65], v[72:73], 1.0 op_sel_hi:[1,0]
	s_waitcnt vmcnt(6)
	v_pk_fma_f32 v[60:61], v[116:117], v[60:61], v[76:77]
	v_pk_mul_f32 v[116:117], v[118:119], v[28:29] op_sel_hi:[1,0]
	s_waitcnt vmcnt(5)
	v_pk_fma_f32 v[120:121], v[64:65], v[120:121], v[80:81]
	v_pk_mul_f32 v[122:123], v[66:67], v[122:123]
	v_pk_add_f32 v[64:65], v[74:75], 1.0 op_sel_hi:[1,0]
	v_pk_mul_f32 v[116:117], v[116:117], v[62:63]
	v_pk_add_f32 v[118:119], v[70:71], 1.0 op_sel_hi:[1,0]
	v_pk_fma_f32 v[122:123], v[64:65], v[122:123], v[82:83]
	v_pk_fma_f32 v[62:63], v[116:117], v[118:119], v[78:79]
	v_cvt_pk_bf16_f32 v116, v120, v121
	v_cvt_pk_bf16_f32 v117, v122, v123
	v_cvt_pk_bf16_f32 v118, v60, v61
	v_cvt_pk_bf16_f32 v119, v62, v63
	global_store_dwordx4 v[24:25], v[116:119], off offset:1024
	v_lshl_add_u64 v[24:25], v[24:25], 0, s[8:9]
	s_andn2_b64 exec, exec, s[4:5]
	s_cbranch_execnz .LBB0_188
.Lnorm_done_b:
.LBB0_189:
	s_or_b64 exec, exec, s[0:1]
	s_getreg_b32 s6, hwreg(HW_REG_XCC_ID, 0, 4)
	s_waitcnt vmcnt(0)
	s_barrier
	s_mov_b64 s[0:1], exec
	v_readlane_b32 s4, v253, 9
	v_readlane_b32 s5, v253, 10
	s_and_b64 s[4:5], s[0:1], s[4:5]
	s_mov_b64 exec, s[4:5]
	s_cbranch_execz .LBB0_219
	v_readlane_b32 s4, v253, 43
	s_lshl_b32 s6, s6, 8
	v_readlane_b32 s5, v253, 44
	s_and_b32 s6, s6, 0xf00
	s_add_u32 s13, s4, s6
	s_addc_u32 s12, s5, 0
	v_mov_b32_e32 v0, s13
	v_add_co_u32_e32 v2, vcc, 0x1000, v0
	v_mov_b32_e32 v0, s12
	s_nop 0
	v_addc_co_u32_e32 v3, vcc, 0, v0, vcc
	s_waitcnt vmcnt(0) expcnt(0) lgkmcnt(0)
	ds_read_b32 v4, v156
	ds_read_b32 v1, v157
	flat_atomic_add v2, v[2:3], v158 offset:1024 sc0
	s_waitcnt lgkmcnt(0)
	v_cvt_f32_u32_e32 v0, v4
	v_sub_u32_e32 v3, 0, v4
	v_rcp_iflag_f32_e32 v0, v0
	s_nop 0
	v_mul_f32_e32 v0, 0x4f7ffffe, v0
	v_cvt_u32_f32_e32 v0, v0
	v_mul_lo_u32 v3, v3, v0
	v_mul_hi_u32 v3, v0, v3
	v_add_u32_e32 v0, v0, v3
	s_waitcnt vmcnt(0)
	v_mul_hi_u32 v0, v2, v0
	v_mul_lo_u32 v3, v0, v4
	v_sub_u32_e32 v3, v2, v3
	v_add_u32_e32 v5, 1, v0
	v_cmp_ge_u32_e32 vcc, v3, v4
	v_add_u32_e32 v2, 1, v2
	s_nop 0
	v_cndmask_b32_e32 v0, v0, v5, vcc
	v_sub_u32_e32 v5, v3, v4
	v_cndmask_b32_e32 v3, v3, v5, vcc
	v_add_u32_e32 v5, 1, v0
	v_cmp_ge_u32_e32 vcc, v3, v4
	s_nop 1
	v_cndmask_b32_e32 v0, v0, v5, vcc
	v_mul_lo_u32 v3, v4, v0
	v_add_u32_e32 v3, v3, v4
	v_cmp_ne_u32_e32 vcc, v2, v3
	s_and_saveexec_b64 s[6:7], vcc
	s_xor_b64 s[6:7], exec, s[6:7]
	s_cbranch_execz .LBB0_203
	v_mov_b32_e32 v1, s13
	v_add_co_u32_e32 v2, vcc, 0x2000, v1
	v_mov_b32_e32 v1, s12
	s_nop 0
	v_addc_co_u32_e32 v3, vcc, 0, v1, vcc
	flat_load_dword v1, v[2:3] offset:1024 sc1
	s_add_u32 s10, s13, 0x2400
	s_addc_u32 s11, s12, 0
	s_waitcnt vmcnt(0) lgkmcnt(0)
	v_cmp_eq_u32_e32 vcc, v1, v0
	s_and_saveexec_b64 s[8:9], vcc
	s_cbranch_execz .LBB0_202
	s_mov_b32 s23, 1
	s_mov_b64 s[14:15], 0
	s_branch .LBB0_194

.LBB0_624:
	s_or_b64 exec, exec, s[0:1]
	v_mov_b32_e32 v0, v154
	v_mov_b32_e32 v2, v154
	s_waitcnt lgkmcnt(0)
	s_barrier
	v_readlane_b32 s0, v253, 0
	v_readfirstlane_b32 s1, v2
	s_ashr_i32 s1, s1, 6
	s_lshl_b32 s0, s0, 3
	s_and_b32 s1, s1, -4
	v_lshrrev_b32_e32 v1, 6, v0
	s_add_i32 s1, s1, s0
	v_and_or_b32 v16, v1, 3, s1
	s_movk_i32 s0, 0x4000
	v_cmp_gt_i32_e32 vcc, s0, v16
	s_and_saveexec_b64 s[0:1], vcc
	v_readlane_b32 s26, v254, 47
	v_readlane_b32 s36, v254, 49
	s_movk_i32 s6, 0x3fff
	v_readlane_b32 s27, v254, 48
	v_readlane_b32 s37, v254, 50
	s_cbranch_execz .LBB0_627
	v_readlane_b32 s4, v254, 58
	v_readlane_b32 s5, v254, 59
	v_readlane_b32 s8, v253, 1
	s_lshl_b64 s[4:5], s[4:5], 2
	v_readlane_b32 s12, v253, 5
	v_readlane_b32 s13, v253, 6
	s_add_u32 s4, s12, s4
	v_and_b32_e32 v2, 63, v0
	s_addc_u32 s5, s13, s5
	v_lshlrev_b32_e32 v136, 5, v2
	v_lshl_add_u64 v[18:19], s[4:5], 0, v[136:137]
	v_readlane_b32 s4, v254, 55
	v_lshlrev_b32_e32 v0, 2, v2
	v_readlane_b32 s5, v254, 56
	v_xor_b32_e32 v29, 64, v0
	v_xor_b32_e32 v34, 0x80, v0
	v_lshl_add_u64 v[0:1], s[4:5], 0, v[136:137]
	s_mov_b64 s[4:5], 0x7000
	v_lshl_add_u64 v[20:21], v[0:1], 0, s[4:5]
	s_mov_b64 s[4:5], 0x6000
	v_ashrrev_i32_e32 v17, 31, v16
	v_lshl_add_u64 v[22:23], v[0:1], 0, s[4:5]
	v_lshlrev_b64 v[0:1], 11, v[16:17]
	v_readlane_b32 s4, v253, 47
	v_lshl_or_b32 v0, v2, 4, v0
	v_readlane_b32 s5, v253, 48
	v_readlane_b32 s9, v253, 2
	v_readlane_b32 s10, v253, 3
	v_lshl_add_u64 v[24:25], s[4:5], 0, v[0:1]
	v_lshlrev_b64 v[0:1], 12, v[16:17]
	v_or_b32_e32 v0, v0, v136
	v_lshl_add_u64 v[26:27], s[70:71], 0, v[0:1]
	s_mov_b64 s[4:5], 0
	v_readlane_b32 s11, v253, 4
	v_readlane_b32 s14, v253, 7
	v_readlane_b32 s15, v253, 8
	global_load_dwordx4 v[8:11], v[26:27], off offset:16
	global_load_dwordx4 v[12:15], v[26:27], off
	global_load_dwordx4 v[4:7], v[26:27], off offset:2048
	global_load_dwordx4 v[0:3], v[26:27], off offset:2064
	v_lshl_add_u64 v[26:27], v[26:27], 0, s[36:37]
	s_sub_u32 s64, 0, s36
	v_mov_b32_e32 v134, s64
.LBB0_626:
	v_ashrrev_i32_e32 v30, 11, v16
	v_mul_hi_i32_i24_e32 v31, 0x2400, v30
	v_mul_i32_i24_e32 v30, 0x2400, v30
	v_lshlrev_b64 v[30:31], 2, v[30:31]
	v_lshl_add_u64 v[32:33], v[20:21], 0, v[30:31]
	v_lshl_add_u64 v[30:31], v[22:23], 0, v[30:31]
	global_load_dwordx4 v[36:39], v[18:19], off offset:16
	global_load_dwordx4 v[40:43], v[18:19], off
	global_load_dwordx4 v[44:47], v[32:33], off offset:16
	global_load_dwordx4 v[48:51], v[32:33], off
	global_load_dwordx4 v[52:55], v[30:31], off offset:16
	global_load_dwordx4 v[56:59], v[30:31], off
	global_load_dwordx4 v[60:63], v[18:19], off offset:2064
	global_load_dwordx4 v[64:67], v[18:19], off offset:2048
	global_load_dwordx4 v[68:71], v[32:33], off offset:2064
	global_load_dwordx4 v[72:75], v[32:33], off offset:2048
	global_load_dwordx4 v[76:79], v[30:31], off offset:2064
	global_load_dwordx4 v[80:83], v[30:31], off offset:2048
	v_add_u32_e32 v16, s20, v16
	v_cmp_lt_i32_e32 vcc, s6, v16
	s_or_b64 s[4:5], vcc, s[4:5]
	s_nop 0
	v_cndmask_b32_e32 v132, 0, v134, vcc
	v_cndmask_b32_e64 v133, 0, -1, vcc
	v_lshl_add_u64 v[132:133], v[26:27], 0, v[132:133]
	global_load_dwordx4 v[124:127], v[132:133], off offset:16
	global_load_dwordx4 v[128:131], v[132:133], off
	global_load_dwordx4 v[120:123], v[132:133], off offset:2048
	global_load_dwordx4 v[116:119], v[132:133], off offset:2064
	v_lshl_add_u64 v[26:27], v[26:27], 0, s[36:37]
	s_waitcnt vmcnt(16)
	v_mul_f32_e32 v85, v9, v9
	v_mul_f32_e32 v84, v13, v13
	v_fmac_f32_e32 v84, v12, v12
	v_fmac_f32_e32 v85, v8, v8
	v_fmac_f32_e32 v84, v14, v14
	v_fmac_f32_e32 v85, v10, v10
	v_fmac_f32_e32 v84, v15, v15
	v_fmac_f32_e32 v85, v11, v11
	v_add_f32_e32 v17, v84, v85
	v_mov_b32_e32 v32, v5
	v_mov_b32_e32 v33, v1
	v_mov_b32_e32 v30, v4
	v_mov_b32_e32 v31, v0
	v_pk_mul_f32 v[32:33], v[32:33], v[32:33]
	s_nop 0
	v_pk_fma_f32 v[30:31], v[30:31], v[30:31], v[32:33]
	v_mov_b32_e32 v32, v6
	v_mov_b32_e32 v33, v2
	v_pk_fma_f32 v[30:31], v[32:33], v[32:33], v[30:31]
	v_mov_b32_e32 v32, v7
	v_mov_b32_e32 v33, v3
	v_pk_fma_f32 v[30:31], v[32:33], v[32:33], v[30:31]
	s_nop 0
	v_add_f32_e32 v17, v17, v30
	v_add_f32_e32 v17, v17, v31
	s_nop 1
	v_add_f32_dpp v17, v17, v17 quad_perm:[1,0,3,2] row_mask:0xf bank_mask:0xf bound_ctrl:1
	s_nop 0
	s_nop 0
	v_add_f32_dpp v17, v17, v17 quad_perm:[2,3,0,1] row_mask:0xf bank_mask:0xf bound_ctrl:1
	s_nop 0
	s_nop 0
	v_add_f32_dpp v17, v17, v17 row_half_mirror row_mask:0xf bank_mask:0xf bound_ctrl:1
	s_nop 1
	v_add_f32_dpp v17, v17, v17 row_mirror row_mask:0xf bank_mask:0xf bound_ctrl:1
	ds_bpermute_b32 v28, v29, v17
	s_waitcnt lgkmcnt(0)
	v_add_f32_e32 v17, v17, v28
	ds_bpermute_b32 v28, v34, v17
	s_waitcnt lgkmcnt(0)
	v_add_f32_e32 v17, v17, v28
	v_fmamk_f32 v17, v17, 0x3a800000, v155
	v_rsq_f32_e32 v28, v17
	s_nop 0
	v_pk_mul_f32 v[8:9], v[8:9], v[28:29] op_sel_hi:[1,0]
	v_pk_mul_f32 v[12:13], v[12:13], v[28:29] op_sel_hi:[1,0]
	v_pk_mul_f32 v[14:15], v[14:15], v[28:29] op_sel_hi:[1,0]
	v_pk_mul_f32 v[0:1], v[0:1], v[28:29] op_sel_hi:[1,0]
	v_pk_mul_f32 v[4:5], v[4:5], v[28:29] op_sel_hi:[1,0]
	v_pk_mul_f32 v[6:7], v[6:7], v[28:29] op_sel_hi:[1,0]
	s_waitcnt vmcnt(15)
	v_pk_mul_f32 v[8:9], v[36:37], v[8:9]
	s_waitcnt vmcnt(14)
	v_pk_mul_f32 v[12:13], v[40:41], v[12:13]
	s_waitcnt vmcnt(13)
	v_pk_add_f32 v[36:37], v[44:45], 1.0 op_sel_hi:[1,0]
	s_waitcnt vmcnt(12)
	v_pk_add_f32 v[40:41], v[48:49], 1.0 op_sel_hi:[1,0]
	s_waitcnt vmcnt(11)
	v_pk_fma_f32 v[36:37], v[36:37], v[8:9], v[52:53]
	v_pk_mul_f32 v[8:9], v[10:11], v[28:29] op_sel_hi:[1,0]
	s_waitcnt vmcnt(10)
	v_pk_fma_f32 v[12:13], v[40:41], v[12:13], v[56:57]
	v_pk_mul_f32 v[14:15], v[42:43], v[14:15]
	v_pk_add_f32 v[40:41], v[50:51], 1.0 op_sel_hi:[1,0]
	v_pk_mul_f32 v[8:9], v[38:39], v[8:9]
	v_pk_add_f32 v[10:11], v[46:47], 1.0 op_sel_hi:[1,0]
	v_pk_fma_f32 v[14:15], v[40:41], v[14:15], v[58:59]
	v_pk_fma_f32 v[38:39], v[10:11], v[8:9], v[54:55]
	v_cvt_pk_bf16_f32 v8, v12, v13
	v_cvt_pk_bf16_f32 v9, v14, v15
	v_cvt_pk_bf16_f32 v10, v36, v37
	v_cvt_pk_bf16_f32 v11, v38, v39
	global_store_dwordx4 v[24:25], v[8:11], off
	s_waitcnt vmcnt(10)
	v_pk_mul_f32 v[0:1], v[0:1], v[60:61]
	s_waitcnt vmcnt(9)
	v_pk_mul_f32 v[4:5], v[64:65], v[4:5]
	s_waitcnt vmcnt(8)
	v_pk_add_f32 v[60:61], v[68:69], 1.0 op_sel_hi:[1,0]
	s_waitcnt vmcnt(7)
	v_pk_add_f32 v[64:65], v[72:73], 1.0 op_sel_hi:[1,0]
	s_waitcnt vmcnt(6)
	v_pk_fma_f32 v[60:61], v[0:1], v[60:61], v[76:77]
	v_pk_mul_f32 v[0:1], v[2:3], v[28:29] op_sel_hi:[1,0]
	s_waitcnt vmcnt(5)
	v_pk_fma_f32 v[4:5], v[64:65], v[4:5], v[80:81]
	v_pk_mul_f32 v[6:7], v[66:67], v[6:7]
	v_pk_add_f32 v[64:65], v[74:75], 1.0 op_sel_hi:[1,0]
	v_pk_mul_f32 v[0:1], v[0:1], v[62:63]
	v_pk_add_f32 v[2:3], v[70:71], 1.0 op_sel_hi:[1,0]
	v_pk_fma_f32 v[6:7], v[64:65], v[6:7], v[82:83]
	v_pk_fma_f32 v[62:63], v[0:1], v[2:3], v[78:79]
	v_cvt_pk_bf16_f32 v0, v4, v5
	v_cvt_pk_bf16_f32 v1, v6, v7
	v_cvt_pk_bf16_f32 v2, v60, v61
	v_cvt_pk_bf16_f32 v3, v62, v63
	global_store_dwordx4 v[24:25], v[0:3], off offset:1024
	v_lshl_add_u64 v[24:25], v[24:25], 0, s[26:27]
	s_andn2_b64 exec, exec, s[4:5]
	s_cbranch_execz .Lnorm_done_c
	v_ashrrev_i32_e32 v30, 11, v16
	v_mul_hi_i32_i24_e32 v31, 0x2400, v30
	v_mul_i32_i24_e32 v30, 0x2400, v30
	v_lshlrev_b64 v[30:31], 2, v[30:31]
	v_lshl_add_u64 v[32:33], v[20:21], 0, v[30:31]
	v_lshl_add_u64 v[30:31], v[22:23], 0, v[30:31]
	global_load_dwordx4 v[36:39], v[18:19], off offset:16
	global_load_dwordx4 v[40:43], v[18:19], off
	global_load_dwordx4 v[44:47], v[32:33], off offset:16
	global_load_dwordx4 v[48:51], v[32:33], off
	global_load_dwordx4 v[52:55], v[30:31], off offset:16
	global_load_dwordx4 v[56:59], v[30:31], off
	global_load_dwordx4 v[60:63], v[18:19], off offset:2064
	global_load_dwordx4 v[64:67], v[18:19], off offset:2048
	global_load_dwordx4 v[68:71], v[32:33], off offset:2064
	global_load_dwordx4 v[72:75], v[32:33], off offset:2048
	global_load_dwordx4 v[76:79], v[30:31], off offset:2064
	global_load_dwordx4 v[80:83], v[30:31], off offset:2048
	v_add_u32_e32 v16, s20, v16
	v_cmp_lt_i32_e32 vcc, s6, v16
	s_or_b64 s[4:5], vcc, s[4:5]
	s_nop 0
	v_cndmask_b32_e32 v132, 0, v134, vcc
	v_cndmask_b32_e64 v133, 0, -1, vcc
	v_lshl_add_u64 v[132:133], v[26:27], 0, v[132:133]
	global_load_dwordx4 v[8:11], v[132:133], off offset:16
	global_load_dwordx4 v[12:15], v[132:133], off
	global_load_dwordx4 v[4:7], v[132:133], off offset:2048
	global_load_dwordx4 v[0:3], v[132:133], off offset:2064
	v_lshl_add_u64 v[26:27], v[26:27], 0, s[36:37]
	s_waitcnt vmcnt(16)
	v_mul_f32_e32 v85, v125, v125
	v_mul_f32_e32 v84, v129, v129
	v_fmac_f32_e32 v84, v128, v128
	v_fmac_f32_e32 v85, v124, v124
	v_fmac_f32_e32 v84, v130, v130
	v_fmac_f32_e32 v85, v126, v126
	v_fmac_f32_e32 v84, v131, v131
	v_fmac_f32_e32 v85, v127, v127
	v_add_f32_e32 v17, v84, v85
	v_mov_b32_e32 v32, v121
	v_mov_b32_e32 v33, v117
	v_mov_b32_e32 v30, v120
	v_mov_b32_e32 v31, v116
	v_pk_mul_f32 v[32:33], v[32:33], v[32:33]
	s_nop 0
	v_pk_fma_f32 v[30:31], v[30:31], v[30:31], v[32:33]
	v_mov_b32_e32 v32, v122
	v_mov_b32_e32 v33, v118
	v_pk_fma_f32 v[30:31], v[32:33], v[32:33], v[30:31]
	v_mov_b32_e32 v32, v123
	v_mov_b32_e32 v33, v119
	v_pk_fma_f32 v[30:31], v[32:33], v[32:33], v[30:31]
	s_nop 0
	v_add_f32_e32 v17, v17, v30
	v_add_f32_e32 v17, v17, v31
	s_nop 1
	v_add_f32_dpp v17, v17, v17 quad_perm:[1,0,3,2] row_mask:0xf bank_mask:0xf bound_ctrl:1
	s_nop 0
	s_nop 0
	v_add_f32_dpp v17, v17, v17 quad_perm:[2,3,0,1] row_mask:0xf bank_mask:0xf bound_ctrl:1
	s_nop 0
	s_nop 0
	v_add_f32_dpp v17, v17, v17 row_half_mirror row_mask:0xf bank_mask:0xf bound_ctrl:1
	s_nop 1
	v_add_f32_dpp v17, v17, v17 row_mirror row_mask:0xf bank_mask:0xf bound_ctrl:1
	ds_bpermute_b32 v28, v29, v17
	s_waitcnt lgkmcnt(0)
	v_add_f32_e32 v17, v17, v28
	ds_bpermute_b32 v28, v34, v17
	s_waitcnt lgkmcnt(0)
	v_add_f32_e32 v17, v17, v28
	v_fmamk_f32 v17, v17, 0x3a800000, v155
	v_rsq_f32_e32 v28, v17
	s_nop 0
	v_pk_mul_f32 v[124:125], v[124:125], v[28:29] op_sel_hi:[1,0]
	v_pk_mul_f32 v[128:129], v[128:129], v[28:29] op_sel_hi:[1,0]
	v_pk_mul_f32 v[130:131], v[130:131], v[28:29] op_sel_hi:[1,0]
	v_pk_mul_f32 v[116:117], v[116:117], v[28:29] op_sel_hi:[1,0]
	v_pk_mul_f32 v[120:121], v[120:121], v[28:29] op_sel_hi:[1,0]
	v_pk_mul_f32 v[122:123], v[122:123], v[28:29] op_sel_hi:[1,0]
	s_waitcnt vmcnt(15)
	v_pk_mul_f32 v[124:125], v[36:37], v[124:125]
	s_waitcnt vmcnt(14)
	v_pk_mul_f32 v[128:129], v[40:41], v[128:129]
	s_waitcnt vmcnt(13)
	v_pk_add_f32 v[36:37], v[44:45], 1.0 op_sel_hi:[1,0]
	s_waitcnt vmcnt(12)
	v_pk_add_f32 v[40:41], v[48:49], 1.0 op_sel_hi:[1,0]
	s_waitcnt vmcnt(11)
	v_pk_fma_f32 v[36:37], v[36:37], v[124:125], v[52:53]
	v_pk_mul_f32 v[124:125], v[126:127], v[28:29] op_sel_hi:[1,0]
	s_waitcnt vmcnt(10)
	v_pk_fma_f32 v[128:129], v[40:41], v[128:129], v[56:57]
	v_pk_mul_f32 v[130:131], v[42:43], v[130:131]
	v_pk_add_f32 v[40:41], v[50:51], 1.0 op_sel_hi:[1,0]
	v_pk_mul_f32 v[124:125], v[38:39], v[124:125]
	v_pk_add_f32 v[126:127], v[46:47], 1.0 op_sel_hi:[1,0]
	v_pk_fma_f32 v[130:131], v[40:41], v[130:131], v[58:59]
	v_pk_fma_f32 v[38:39], v[126:127], v[124:125], v[54:55]
	v_cvt_pk_bf16_f32 v124, v128, v129
	v_cvt_pk_bf16_f32 v125, v130, v131
	v_cvt_pk_bf16_f32 v126, v36, v37
	v_cvt_pk_bf16_f32 v127, v38, v39
	global_store_dwordx4 v[24:25], v[124:127], off
	s_waitcnt vmcnt(10)
	v_pk_mul_f32 v[116:117], v[116:117], v[60:61]
	s_waitcnt vmcnt(9)
	v_pk_mul_f32 v[120:121], v[64:65], v[120:121]
	s_waitcnt vmcnt(8)
	v_pk_add_f32 v[60:61], v[68:69], 1.0 op_sel_hi:[1,0]
	s_waitcnt vmcnt(7)
	v_pk_add_f32 v[64:65], v[72:73], 1.0 op_sel_hi:[1,0]
	s_waitcnt vmcnt(6)
	v_pk_fma_f32 v[60:61], v[116:117], v[60:61], v[76:77]
	v_pk_mul_f32 v[116:117], v[118:119], v[28:29] op_sel_hi:[1,0]
	s_waitcnt vmcnt(5)
	v_pk_fma_f32 v[120:121], v[64:65], v[120:121], v[80:81]
	v_pk_mul_f32 v[122:123], v[66:67], v[122:123]
	v_pk_add_f32 v[64:65], v[74:75], 1.0 op_sel_hi:[1,0]
	v_pk_mul_f32 v[116:117], v[116:117], v[62:63]
	v_pk_add_f32 v[118:119], v[70:71], 1.0 op_sel_hi:[1,0]
	v_pk_fma_f32 v[122:123], v[64:65], v[122:123], v[82:83]
	v_pk_fma_f32 v[62:63], v[116:117], v[118:119], v[78:79]
	v_cvt_pk_bf16_f32 v116, v120, v121
	v_cvt_pk_bf16_f32 v117, v122, v123
	v_cvt_pk_bf16_f32 v118, v60, v61
	v_cvt_pk_bf16_f32 v119, v62, v63
	global_store_dwordx4 v[24:25], v[116:119], off offset:1024
	v_lshl_add_u64 v[24:25], v[24:25], 0, s[26:27]
	s_andn2_b64 exec, exec, s[4:5]
	s_cbranch_execnz .LBB0_626
